# pipelined prompt attention loop with split K/V prefetch (K three tiles ahead, V two tiles ahead, one vmcnt(8) per tile)
# speedup vs baseline: 1.0082x; 1.0001x over previous
; __device__ __forceinline__ int pi32(int r) { return (r & ~12) | ((r & 4) << 1) | ((r & 8) >> 1); }
; #define AT_DMA(tr) do { const unsigned sb_ = (unsigned)__builtin_amdgcn_readfirstlane(dk + (((tr) & (NSTG - 1)) * STAGE)); const size_t ko_ = (size_t)(tr) * 26 * 4096, vo_ = (size_t)(tr) * 640 * 64; \
;         glds16(kg + ko_, sb_ + OFF_K0); if (!WIN) glds16(kg + ko_ + 4096, sb_ + OFF_K1); glds16(vg + vo_, sb_ + OFF_V); if (!WIN) glds16(vg + vo_ + 64 * 64, sb_ + OFF_V + 8192); } while (0)
; template <bool WIN> ...
;     ...
;     const bf16_t* kg = QK + ((size_t)((seq_base >> 6) + t_lo) * 26 * 64 + drow) * 64 + dch * 8 + kcol0 * 64;
;     const bf16_t* vg = VT + ((size_t)((seq_base >> 6) + t_lo) * 640 + vrow0 + drow) * 64 + dch * 8;
;     const unsigned dk = ldsb + wid * 1024;
;     ...
;     constexpr int NPW = WIN ? 2 : 4;
;     bf16x8 qfr[4];
;     { const int qrow = seq_base + qw + l31; const bf16_t* qp = QK + ((size_t)((qrow >> 6) * 26 + (qcol >> 6)) * 64 + (qrow & 63)) * 64 + hi * 8;
; #pragma unroll
;       for (int ds = 0; ds < 4; ++ds) qfr[ds] = *(const bf16x8*)(qp + ds * 16); }
;     ...
;     AT_DMA(0); if (NT > 1) AT_DMA(1); if (NT > 2) AT_DMA(2);
;     constexpr float THR = 8.0f;
;     float m_ref = WIN ? sinkp[2 * hsel + half] * LOG2E : 0.f;
;     float l_run = (WIN && hi == 0) ? 1.f : 0.f;
;     float cbase = 0.f;
;     f32x16 cvec;
; #pragma unroll
;     for (int r = 0; r < 16; ++r) cvec[r] = cbase - m_ref;
;     f32x16 o[NDB];
; #pragma unroll
;     for (int db = 0; db < NDB; ++db)
; #pragma unroll
;         for (int r = 0; r < 16; ++r) o[db][r] = 0.f;
;     const int krow = pi32(l31), fK = (krow >> 1) & 7, fV = (l31 >> 1) & 7;
;     int kx[4], vx[4];
; #pragma unroll
;     for (int c = 0; c < 4; ++c) { kx[c] = (WIN ? OFF_K0 : (half ? OFF_K1 : OFF_K0)) + krow * 128 + (((2 * c + hi) ^ fK) << 4); vx[c] = OFF_V + l31 * 128 + (((2 * c + hi) ^ fV) << 4); }
.LBB0_244:
	s_lshl_b32 s62, s33, 5
	s_lshl_b32 s20, s33, 2
	s_and_b32 s62, s62, 32
	v_readfirstlane_b32 s64, v230
	s_and_b32 s20, s20, 24
	s_add_i32 s62, s62, s22
	s_bfe_u32 s77, s64, 0x20006
	s_or_b32 s20, s20, s24
	s_lshl_b32 s62, s62, 7
	s_lshl_b32 s82, s77, 5
	s_lshl_b32 s20, s20, 11
	s_or_b32 s78, s82, s62
	s_and_b32 s20, s20, 0xe000
	s_lshr_b32 s76, s64, 8
	v_or_b32_e32 v4, s78, v185
	v_add_u32_e32 v170, s20, v4
	s_add_i32 s62, s76, s66
	v_ashrrev_i32_e32 v2, 6, v170
	v_mov_b32_e32 v0, s62
	v_mad_u64_u32 v[2:3], s[62:63], v2, 26, v[0:1]
	v_ashrrev_i32_e32 v3, 31, v2
	v_lshlrev_b64 v[2:3], 13, v[2:3]
	v_lshlrev_b32_e32 v0, 7, v4
	v_lshl_add_u64 v[2:3], s[6:7], 0, v[2:3]
	v_and_b32_e32 v4, 0x1f80, v0
	v_mov_b32_e32 v5, v1
	v_lshl_add_u64 v[2:3], v[2:3], 0, v[4:5]
	v_lshl_add_u64 v[2:3], v[2:3], 0, v[164:165]
	global_load_dwordx4 v[114:117], v[2:3], off offset:96
	global_load_dwordx4 v[118:121], v[2:3], off offset:64
	global_load_dwordx4 v[122:125], v[2:3], off offset:32
	global_load_dwordx4 v[126:129], v[2:3], off
	s_lshl_b32 s62, s31, 11
	s_and_b32 s62, s62, 0xffffc000
	s_or_b32 s62, s26, s62
	v_cndmask_b32_e64 v0, 0, 1, s[38:39]
	s_lshr_b32 s81, s62, 13
	v_readfirstlane_b32 s62, v0
	s_lshr_b32 s63, s64, 4
	s_lshl_b32 s83, s62, 12
	s_lshr_b32 s62, s64, 6
	s_and_b32 s63, s63, 4
	s_lshl_b32 s84, s62, 3
	v_bitop3_b32 v4, s63, v186, v189 bitop3:0x36
	s_lshr_b32 s63, s20, 6
	v_or_b32_e32 v0, s84, v188
	s_mul_i32 s20, s63, 0x680
	v_lshl_add_u64 v[2:3], s[20:21], 0, v[0:1]
	v_lshlrev_b64 v[2:3], 7, v[2:3]
	v_lshl_add_u64 v[2:3], s[6:7], 0, v[2:3]
	v_lshlrev_b32_e32 v4, 4, v4
	v_lshl_add_u64 v[2:3], v[2:3], 0, v[4:5]
	s_mul_i32 s20, s63, 0x280
	v_add_u32_e32 v6, s12, v0
	v_mov_b32_e32 v7, v1
	v_lshl_add_u64 v[2:3], v[2:3], 0, s[18:19]
	v_lshl_add_u64 v[6:7], v[6:7], 0, s[20:21]
	s_lshl_b32 s20, s62, 10
	s_mov_b64 s[62:63], 0x24000
	v_lshl_add_u64 v[8:9], v[2:3], 0, s[62:63]
	s_add_i32 s20, s20, 0
	s_mov_b32 s62, m0
	s_mov_b32 m0, s20
	s_nop 0
	global_load_lds_dwordx4 v[8:9], off
	s_mov_b32 m0, s62
	s_mov_b64 s[62:63], 0x26000
	v_lshlrev_b64 v[6:7], 7, v[6:7]
	v_lshl_add_u64 v[8:9], v[2:3], 0, s[62:63]
	s_add_i32 s62, s20, 0x2000
	v_lshl_add_u64 v[6:7], s[4:5], 0, v[6:7]
	s_mov_b32 s63, m0
	s_mov_b32 m0, s62
	s_nop 0
	global_load_lds_dwordx4 v[8:9], off
	s_mov_b32 m0, s63
	s_add_i32 s62, s20, 0x4000
	v_lshl_add_u64 v[6:7], v[6:7], 0, v[4:5]
	s_mov_b32 s63, m0
	s_mov_b32 m0, s62
	s_nop 0
	global_load_lds_dwordx4 v[6:7], off
	s_mov_b32 m0, s63
	s_add_i32 s62, s20, 0x6000
	v_lshl_add_u64 v[8:9], v[6:7], 0, s[40:41]
	s_mov_b32 s63, m0
	s_mov_b32 m0, s62
	s_nop 0
	global_load_lds_dwordx4 v[8:9], off
	s_mov_b32 m0, s63
	s_add_i32 s62, s20, 0x8000
	v_lshl_add_u64 v[8:9], v[2:3], 0, s[42:43]
	s_mov_b32 s63, m0
	s_mov_b32 m0, s62
	s_nop 0
	global_load_lds_dwordx4 v[8:9], off
	s_mov_b32 m0, s63
	s_add_i32 s62, s20, 0xa000
	v_lshl_add_u64 v[8:9], v[2:3], 0, s[46:47]
	s_mov_b32 s63, m0
	s_mov_b32 m0, s62
	s_nop 0
	global_load_lds_dwordx4 v[8:9], off
	s_mov_b32 m0, s63
	s_add_i32 s62, s20, 0xc000
	v_lshl_add_u64 v[8:9], v[6:7], 0, s[48:49]
	s_mov_b32 s63, m0
	s_mov_b32 m0, s62
	s_nop 0
	global_load_lds_dwordx4 v[8:9], off
	s_mov_b32 m0, s63
	s_add_i32 s62, s20, 0xe000
	v_lshl_add_u64 v[8:9], v[6:7], 0, s[50:51]
	s_mov_b32 s63, m0
	s_mov_b32 m0, s62
	s_nop 0
	global_load_lds_dwordx4 v[8:9], off
	s_mov_b32 m0, s63
	s_add_i32 s62, s20, 0x10000
	v_lshl_add_u64 v[8:9], v[2:3], 0, s[52:53]
	s_mov_b32 s63, m0
	s_mov_b32 m0, s62
	s_nop 0
	global_load_lds_dwordx4 v[8:9], off
	s_mov_b32 m0, s63
	s_add_i32 s62, s20, 0x12000
	v_lshl_add_u64 v[2:3], v[2:3], 0, s[54:55]
	s_mov_b32 s63, m0
	s_mov_b32 m0, s62
	s_nop 0
	global_load_lds_dwordx4 v[2:3], off
	s_mov_b32 m0, s63
	s_add_i32 s62, s20, 0x14000
	v_lshl_add_u64 v[2:3], v[6:7], 0, s[56:57]
	s_add_i32 s62, s20, 0x16000
	v_lshl_add_u64 v[2:3], v[6:7], 0, s[58:59]
	s_cmpk_lt_u32 s64, 0x100
	s_cselect_b64 s[62:63], -1, 0
	s_and_b64 s[64:65], s[62:63], exec
	s_cselect_b32 s64, 0, 0x2000
	s_add_i32 s67, s27, 0x20000
	v_mov_b32_e32 v2, s67
	ds_read_b32 v3, v2 offset:14336
	ds_read_b32 v2, v2 offset:16124
	v_or_b32_e32 v162, s64, v177
	v_mov_b32_e32 v14, v1
	v_mov_b32_e32 v15, v1
	s_waitcnt lgkmcnt(1)
	v_readfirstlane_b32 s79, v3
	s_waitcnt lgkmcnt(0)
	v_readfirstlane_b32 s80, v2
	v_add_u32_e32 v2, s84, v197
	v_mov_b32_e32 v3, v1
	v_lshlrev_b64 v[2:3], 7, v[2:3]
	v_mad_u64_u32 v[2:3], s[64:65], s81, v199, v[2:3]
	v_or_b32_e32 v2, v2, v4
	v_lshl_add_u64 v[172:173], s[36:37], 0, v[2:3]
	v_lshlrev_b64 v[2:3], 7, v[0:1]
	v_mad_u64_u32 v[2:3], s[64:65], s81, v200, v[2:3]
	s_or_b32 s64, s82, s83
	v_or_b32_e32 v2, v2, v4
	v_add_lshl_u32 v0, s64, v198, 2
	v_lshl_add_u64 v[174:175], s[16:17], 0, v[2:3]
	v_sub_u32_e32 v171, v195, v0
	s_sub_i32 s64, s28, s82
	v_mov_b32_e32 v0, v1
	v_mov_b32_e32 v2, v1
	v_mov_b32_e32 v3, v1
	v_mov_b32_e32 v4, v1
	v_mov_b32_e32 v6, v1
	v_mov_b32_e32 v7, v1
	v_mov_b32_e32 v8, v1
	v_mov_b32_e32 v9, v1
	v_mov_b32_e32 v10, v1
	v_mov_b32_e32 v11, v1
	v_mov_b32_e32 v12, v1
	v_mov_b32_e32 v13, v1
	v_mov_b64_e32 v[64:65], v[14:15]
	v_mov_b64_e32 v[48:49], v[14:15]
	v_mov_b64_e32 v[32:33], v[14:15]
	s_sub_i32 s81, s64, s83
	s_add_i32 s64, s29, s83
	v_mov_b64_e32 v[62:63], v[12:13]
	v_mov_b64_e32 v[60:61], v[10:11]
	v_mov_b64_e32 v[58:59], v[8:9]
	v_mov_b64_e32 v[56:57], v[6:7]
	v_mov_b64_e32 v[54:55], v[4:5]
	v_mov_b64_e32 v[52:53], v[2:3]
	v_mov_b64_e32 v[50:51], v[0:1]
	v_mov_b64_e32 v[46:47], v[12:13]
	v_mov_b64_e32 v[44:45], v[10:11]
	v_mov_b64_e32 v[42:43], v[8:9]
	v_mov_b64_e32 v[40:41], v[6:7]
	v_mov_b64_e32 v[38:39], v[4:5]
	v_mov_b64_e32 v[36:37], v[2:3]
	v_mov_b64_e32 v[34:35], v[0:1]
	v_mov_b64_e32 v[30:31], v[12:13]
	v_mov_b64_e32 v[28:29], v[10:11]
	v_mov_b64_e32 v[26:27], v[8:9]
	v_mov_b64_e32 v[24:25], v[6:7]
	v_mov_b64_e32 v[22:23], v[4:5]
	v_mov_b64_e32 v[20:21], v[2:3]
	v_mov_b64_e32 v[18:19], v[0:1]
	v_mov_b64_e32 v[16:17], v[14:15]
	s_add_i32 s82, s64, s82
	s_mov_b32 s83, 0
	s_mov_b32 s84, 0
	s_mov_b32 s85, 0x10000
	v_mov_b64_e32 v[14:15], v[12:13]
	v_mov_b64_e32 v[12:13], v[10:11]
	v_mov_b64_e32 v[10:11], v[8:9]
	v_mov_b64_e32 v[8:9], v[6:7]
	v_mov_b64_e32 v[6:7], v[4:5]
	v_mov_b64_e32 v[4:5], v[2:3]
	v_mov_b64_e32 v[2:3], v[0:1]
	v_mov_b32_e32 v0, 0
	v_mov_b32_e32 v196, 0
	v_mov_b32_e32 v202, 0
	s_mov_b32 s86, 0
	v_mov_b32_e32 v66, 0
	v_mov_b32_e32 v67, v1
	v_mov_b32_e32 v68, v1
	v_mov_b32_e32 v69, v1
	v_mov_b32_e32 v70, v1
	v_mov_b32_e32 v71, v1
	v_mov_b32_e32 v72, v1
	v_mov_b32_e32 v73, v1
	v_mov_b32_e32 v74, v1
	v_mov_b32_e32 v75, v1
	v_mov_b32_e32 v76, v1
	v_mov_b32_e32 v77, v1
	v_mov_b32_e32 v78, v1
	v_mov_b32_e32 v79, v1
	v_mov_b32_e32 v80, v1
	v_mov_b32_e32 v81, v1
	s_mov_b32 s98, 0xfffec000
	s_mov_b32 s99, -1
	v_lshl_add_u64 v[172:173], v[172:173], 0, s[98:99]
	s_mov_b32 s98, 0xfffcc000
	s_waitcnt vmcnt(10)
	s_branch .LSPp_top
; template <int N> __device__ __forceinline__ void wait_bar() { asm volatile("s_waitcnt vmcnt(%0) lgkmcnt(0)\n\ts_barrier" :: "n"(N) : "memory"); }
; #define AT_DMA(tr) do { const unsigned sb_ = (unsigned)__builtin_amdgcn_readfirstlane(dk + (((tr) & (NSTG - 1)) * STAGE)); const size_t ko_ = (size_t)(tr) * 26 * 4096, vo_ = (size_t)(tr) * 640 * 64; \
;         glds16(kg + ko_, sb_ + OFF_K0); if (!WIN) glds16(kg + ko_ + 4096, sb_ + OFF_K1); glds16(vg + vo_, sb_ + OFF_V); if (!WIN) glds16(vg + vo_ + 64 * 64, sb_ + OFF_V + 8192); } while (0)
; template <bool WIN> ...
;     ...
;     for (int tr = 0; tr < NT; ++tr) {
;         if (tr + 2 < NT) wait_bar<2 * NPW>(); else if (tr + 1 < NT) wait_bar<NPW>(); else wait_bar<0>();
;         if (tr + 3 < NT) AT_DMA(tr + 3);
.LSPp_top:
	s_cmpk_gt_u32 s86, 125
	s_cbranch_scc1 .LSPp_t0
	s_waitcnt vmcnt(8) lgkmcnt(0)
	s_barrier
.LSPp_t0d:
	s_cmpk_gt_u32 s86, 124
	s_cbranch_scc1 .LSPp_skipk
	s_add_i32 s98, s85, 0x8000
	s_and_b32 s98, s98, 0x18000
	s_add_i32 s98, s98, s20
	s_mov_b32 m0, s98
	v_lshl_add_u64 v[82:83], v[174:175], 0, s[40:41]
	global_load_lds_dwordx4 v[174:175], off
	s_add_i32 m0, s98, 0x2000
	s_nop 0
	global_load_lds_dwordx4 v[82:83], off
.LSPp_skipk:
	s_cmpk_gt_u32 s86, 125
	s_cbranch_scc1 .LSPp_skipv
	s_and_b32 s98, s85, 0x18000
	s_add_i32 s98, s98, s20
	s_add_i32 m0, s98, 0x4000
	v_lshl_add_u64 v[82:83], v[172:173], 0, s[40:41]
	global_load_lds_dwordx4 v[172:173], off
	s_add_i32 m0, s98, 0x6000
	s_nop 0
	global_load_lds_dwordx4 v[82:83], off
